# third weight-conversion site in layer-1 gate/up idle blocks (P0 converts 1408 fewer items); MIX1/MIX3 causal-conv row loads software-pipelined one batch ahead
# speedup vs baseline: 1.0686x; 1.0029x over previous
.LBB0_260:
	s_waitcnt vmcnt(0)
	v_and_b32_e32 v90, 63, v137
	v_lshrrev_b32_e32 v89, 6, v137
	s_nop 0
	v_readfirstlane_b32 s100, v89
	v_and_b32_e32 v84, 31, v90
	v_lshrrev_b32_e32 v86, 5, v90
	v_and_b32_e32 v88, 7, v90
	v_lshrrev_b32_e32 v87, 3, v90
	v_lshlrev_b32_e32 v85, 5, v88
	s_mul_i32 s101, s100, 0x2100
	v_mul_u32_u24_e32 v89, 33, v86
	v_add_u32_e32 v89, v89, v84
	v_lshl_add_u32 v81, v89, 2, s101
	v_mul_u32_u24_e32 v89, 0x108, v88
	v_add_u32_e32 v89, v89, v87
	v_lshl_add_u32 v82, v89, 2, s101
	s_lshl_b32 s15, s12, 3
	s_add_i32 s15, s15, s100
	s_cmp_ge_u32 s15, 6400
	s_cbranch_scc1 .Lcv1_done

.Lcv1_nomask:
	ds_write_b32 v81, v0
	ds_write_b32 v81, v1 offset:264
	ds_write_b32 v81, v2 offset:528
	ds_write_b32 v81, v3 offset:792
	ds_write_b32 v81, v4 offset:1056
	ds_write_b32 v81, v5 offset:1320
	ds_write_b32 v81, v6 offset:1584
	ds_write_b32 v81, v7 offset:1848
	ds_write_b32 v81, v8 offset:2112
	ds_write_b32 v81, v9 offset:2376
	ds_write_b32 v81, v10 offset:2640
	ds_write_b32 v81, v11 offset:2904
	ds_write_b32 v81, v12 offset:3168
	ds_write_b32 v81, v13 offset:3432
	ds_write_b32 v81, v14 offset:3696
	ds_write_b32 v81, v15 offset:3960
	ds_write_b32 v81, v16 offset:4224
	ds_write_b32 v81, v17 offset:4488
	ds_write_b32 v81, v18 offset:4752
	ds_write_b32 v81, v19 offset:5016
	ds_write_b32 v81, v20 offset:5280
	ds_write_b32 v81, v21 offset:5544
	ds_write_b32 v81, v22 offset:5808
	ds_write_b32 v81, v23 offset:6072
	ds_write_b32 v81, v24 offset:6336
	ds_write_b32 v81, v25 offset:6600
	ds_write_b32 v81, v26 offset:6864
	ds_write_b32 v81, v27 offset:7128
	ds_write_b32 v81, v28 offset:7392
	ds_write_b32 v81, v29 offset:7656
	ds_write_b32 v81, v30 offset:7920
	ds_write_b32 v81, v31 offset:8184
	ds_read2_b32 v[40:41], v82 offset1:33
	ds_read2_b32 v[42:43], v82 offset0:66 offset1:99
	ds_read2_b32 v[44:45], v82 offset0:132 offset1:165
	ds_read2_b32 v[46:47], v82 offset0:198 offset1:231
	ds_read2_b32 v[48:49], v82 offset0:8 offset1:41
	ds_read2_b32 v[50:51], v82 offset0:74 offset1:107
	ds_read2_b32 v[52:53], v82 offset0:140 offset1:173
	ds_read2_b32 v[54:55], v82 offset0:206 offset1:239
	ds_read2_b32 v[56:57], v82 offset0:16 offset1:49
	ds_read2_b32 v[58:59], v82 offset0:82 offset1:115
	ds_read2_b32 v[60:61], v82 offset0:148 offset1:181
	ds_read2_b32 v[62:63], v82 offset0:214 offset1:247
	ds_read2_b32 v[64:65], v82 offset0:24 offset1:57
	ds_read2_b32 v[66:67], v82 offset0:90 offset1:123
	ds_read2_b32 v[68:69], v82 offset0:156 offset1:189
	ds_read2_b32 v[70:71], v82 offset0:222 offset1:255
	s_waitcnt lgkmcnt(0)
	v_mul_f32_e32 v40, v32, v40
	v_mul_f32_e32 v41, v33, v41
	v_mul_f32_e32 v42, v34, v42
	v_mul_f32_e32 v43, v35, v43
	v_mul_f32_e32 v44, v36, v44
	v_mul_f32_e32 v45, v37, v45
	v_mul_f32_e32 v46, v38, v46
	v_mul_f32_e32 v47, v39, v47
	v_cvt_pk_bf16_f32 v72, v40, v41
	v_cvt_pk_bf16_f32 v73, v42, v43
	v_cvt_pk_bf16_f32 v74, v44, v45
	v_cvt_pk_bf16_f32 v75, v46, v47
	global_store_dwordx4 v83, v[72:75], s[28:29]
	v_add_u32_e32 v83, s101, v83
	v_mul_f32_e32 v48, v32, v48
	v_mul_f32_e32 v49, v33, v49
	v_mul_f32_e32 v50, v34, v50
	v_mul_f32_e32 v51, v35, v51
	v_mul_f32_e32 v52, v36, v52
	v_mul_f32_e32 v53, v37, v53
	v_mul_f32_e32 v54, v38, v54
	v_mul_f32_e32 v55, v39, v55
	v_cvt_pk_bf16_f32 v76, v48, v49
	v_cvt_pk_bf16_f32 v77, v50, v51
	v_cvt_pk_bf16_f32 v78, v52, v53
	v_cvt_pk_bf16_f32 v79, v54, v55
	global_store_dwordx4 v83, v[76:79], s[28:29]
	v_add_u32_e32 v83, s101, v83
	v_mul_f32_e32 v56, v32, v56
	v_mul_f32_e32 v57, v33, v57
	v_mul_f32_e32 v58, v34, v58
	v_mul_f32_e32 v59, v35, v59
	v_mul_f32_e32 v60, v36, v60
	v_mul_f32_e32 v61, v37, v61
	v_mul_f32_e32 v62, v38, v62
	v_mul_f32_e32 v63, v39, v63
	v_cvt_pk_bf16_f32 v72, v56, v57
	v_cvt_pk_bf16_f32 v73, v58, v59
	v_cvt_pk_bf16_f32 v74, v60, v61
	v_cvt_pk_bf16_f32 v75, v62, v63
	global_store_dwordx4 v83, v[72:75], s[28:29]
	v_add_u32_e32 v83, s101, v83
	v_mul_f32_e32 v64, v32, v64
	v_mul_f32_e32 v65, v33, v65
	v_mul_f32_e32 v66, v34, v66
	v_mul_f32_e32 v67, v35, v67
	v_mul_f32_e32 v68, v36, v68
	v_mul_f32_e32 v69, v37, v69
	v_mul_f32_e32 v70, v38, v70
	v_mul_f32_e32 v71, v39, v71
	v_cvt_pk_bf16_f32 v76, v64, v65
	v_cvt_pk_bf16_f32 v77, v66, v67
	v_cvt_pk_bf16_f32 v78, v68, v69
	v_cvt_pk_bf16_f32 v79, v70, v71
	global_store_dwordx4 v83, v[76:79], s[28:29]
	s_add_i32 s15, s15, 2048
	s_cmp_lt_u32 s15, 6400
	s_cbranch_scc1 .Lcv1_loop

.LBB0_345:
	s_movk_i32 s0, 0x180
	s_and_b32 s24, s16, 0xffffffc0
	s_mul_i32 s25, s51, 0x1600
	v_cmp_gt_i32_e32 vcc, s0, v24
	s_movk_i32 s0, 0xff
	s_add_i32 s34, 0, 0x12800
	s_mul_hi_i32 s17, s51, 0x1600
	v_lshlrev_b32_e32 v18, 1, v10
	v_cndmask_b32_e32 v19, v221, v222, vcc
	v_cmp_lt_i32_e64 s[42:43], s0, v24
	s_movk_i32 s0, 0x120
	s_add_u32 s30, s39, s25
	v_add3_u32 v26, 0, v18, v19
	v_mul_lo_u32 v18, v24, s0
	s_addc_u32 s31, s50, s17
	v_add_u32_e32 v27, s34, v18
	v_lshl_add_u64 v[10:11], v[10:11], 1, s[30:31]
	s_mov_b32 s17, -16
	s_mov_b32 s100, 0xfffeb600
	s_mov_b32 s101, -1
	v_lshl_add_u64 v[132:133], v[10:11], 0, s[100:101]
	s_mov_b32 s100, 0x1600
	s_mov_b32 s101, 0
	global_load_dword v142, v[132:133], off
	v_lshl_add_u64 v[132:133], v[132:133], 0, s[100:101]
	global_load_dword v143, v[132:133], off
	v_lshl_add_u64 v[132:133], v[132:133], 0, s[100:101]
	global_load_dword v144, v[132:133], off
	v_lshl_add_u64 v[132:133], v[132:133], 0, s[100:101]
	global_load_dword v145, v[132:133], off
	v_lshl_add_u64 v[132:133], v[132:133], 0, s[100:101]
	global_load_dword v146, v[132:133], off
	v_lshl_add_u64 v[132:133], v[132:133], 0, s[100:101]
	global_load_dword v147, v[132:133], off
	v_lshl_add_u64 v[132:133], v[132:133], 0, s[100:101]
	global_load_dword v148, v[132:133], off
	v_lshl_add_u64 v[132:133], v[132:133], 0, s[100:101]
	global_load_dword v149, v[132:133], off
	v_lshl_add_u64 v[132:133], v[132:133], 0, s[100:101]
	global_load_dword v151, v[132:133], off
	v_lshl_add_u64 v[132:133], v[132:133], 0, s[100:101]
	global_load_dword v152, v[132:133], off
	v_lshl_add_u64 v[132:133], v[132:133], 0, s[100:101]
	global_load_dword v153, v[132:133], off
	v_lshl_add_u64 v[132:133], v[132:133], 0, s[100:101]
	global_load_dword v154, v[132:133], off
	v_lshl_add_u64 v[132:133], v[132:133], 0, s[100:101]
	global_load_dword v155, v[132:133], off
	v_lshl_add_u64 v[132:133], v[132:133], 0, s[100:101]
	global_load_dword v156, v[132:133], off
	v_lshl_add_u64 v[132:133], v[132:133], 0, s[100:101]
	global_load_dword v157, v[132:133], off
	v_lshl_add_u64 v[132:133], v[132:133], 0, s[100:101]
	global_load_dword v158, v[132:133], off
	s_branch .LBB0_347

.LBB0_347:
	s_waitcnt vmcnt(0) lgkmcnt(0)
	v_mov_b32_e32 v23, v142
	v_mov_b32_e32 v40, v143
	v_mov_b32_e32 v20, v144
	v_mov_b32_e32 v21, v145
	v_mov_b32_e32 v38, v146
	v_mov_b32_e32 v39, v147
	v_mov_b32_e32 v36, v148
	v_mov_b32_e32 v37, v149
	v_mov_b32_e32 v34, v151
	v_mov_b32_e32 v35, v152
	v_mov_b32_e32 v32, v153
	v_mov_b32_e32 v33, v154
	v_mov_b32_e32 v30, v155
	v_mov_b32_e32 v31, v156
	v_mov_b32_e32 v29, v157
	v_mov_b32_e32 v28, v158
	s_cmp_ge_i32 s17, 32
	s_cbranch_scc1 .Lmy_cp347_nl
	s_mov_b32 s100, 0x1600
	s_mov_b32 s101, 0
	v_lshl_add_u64 v[132:133], v[10:11], 0, s[100:101]
	global_load_dword v142, v[132:133], off
	v_lshl_add_u64 v[132:133], v[132:133], 0, s[100:101]
	global_load_dword v143, v[132:133], off
	v_lshl_add_u64 v[132:133], v[132:133], 0, s[100:101]
	global_load_dword v144, v[132:133], off
	v_lshl_add_u64 v[132:133], v[132:133], 0, s[100:101]
	global_load_dword v145, v[132:133], off
	v_lshl_add_u64 v[132:133], v[132:133], 0, s[100:101]
	global_load_dword v146, v[132:133], off
	v_lshl_add_u64 v[132:133], v[132:133], 0, s[100:101]
	global_load_dword v147, v[132:133], off
	v_lshl_add_u64 v[132:133], v[132:133], 0, s[100:101]
	global_load_dword v148, v[132:133], off
	v_lshl_add_u64 v[132:133], v[132:133], 0, s[100:101]
	global_load_dword v149, v[132:133], off
	v_lshl_add_u64 v[132:133], v[132:133], 0, s[100:101]
	global_load_dword v151, v[132:133], off
	v_lshl_add_u64 v[132:133], v[132:133], 0, s[100:101]
	global_load_dword v152, v[132:133], off
	v_lshl_add_u64 v[132:133], v[132:133], 0, s[100:101]
	global_load_dword v153, v[132:133], off
	v_lshl_add_u64 v[132:133], v[132:133], 0, s[100:101]
	global_load_dword v154, v[132:133], off
	v_lshl_add_u64 v[132:133], v[132:133], 0, s[100:101]
	global_load_dword v155, v[132:133], off
	v_lshl_add_u64 v[132:133], v[132:133], 0, s[100:101]
	global_load_dword v156, v[132:133], off
	v_lshl_add_u64 v[132:133], v[132:133], 0, s[100:101]
	global_load_dword v157, v[132:133], off
	v_lshl_add_u64 v[132:133], v[132:133], 0, s[100:101]
	global_load_dword v158, v[132:133], off
.Lmy_cp347_nl:
	v_pk_fma_f32 v[12:13], v[0:1], v[12:13], v[8:9]
	v_pk_fma_f32 v[12:13], v[2:3], v[16:17], v[12:13]
	s_nop 0
	v_pk_fma_f32 v[16:17], v[0:1], v[16:17], v[8:9]
	s_nop 0
	v_pk_fma_f32 v[12:13], v[4:5], v[14:15], v[12:13]
	s_nop 0
	v_pk_fma_f32 v[16:17], v[2:3], v[14:15], v[16:17]
	s_nop 0
	v_lshlrev_b32_e32 v22, 16, v23
	v_and_b32_e32 v23, 0xffff0000, v23
	s_nop 0
	v_pk_fma_f32 v[12:13], v[6:7], v[22:23], v[12:13]
	s_nop 0
	v_pk_fma_f32 v[16:17], v[4:5], v[22:23], v[16:17]
	s_nop 0
	s_nop 1
	s_nop 1
	s_nop 1
	s_nop 1
	s_nop 1
	s_nop 1
	v_lshlrev_b32_e32 v18, 16, v40
	v_and_b32_e32 v19, 0xffff0000, v40
	v_pk_fma_f32 v[40:41], v[6:7], v[18:19], v[16:17]
	v_mul_f32_e32 v16, 0xbfb8aa3b, v12
	v_exp_f32_e32 v16, v16
	s_nop 0
	v_add_f32_e32 v16, 1.0, v16
	v_rcp_f32_e32 v16, v16
	s_nop 0
	v_mul_f32_e32 v16, v12, v16
	v_mul_f32_e32 v12, 0xbfb8aa3b, v13
	v_exp_f32_e32 v12, v12
	s_nop 0
	v_add_f32_e32 v12, 1.0, v12
	v_rcp_f32_e32 v42, v12
	v_mul_f32_e32 v12, 0xbfb8aa3b, v40
	v_exp_f32_e32 v12, v12
	s_nop 0
	v_add_f32_e32 v12, 1.0, v12
	v_rcp_f32_e32 v12, v12
	s_nop 0
	v_mul_f32_e32 v17, v40, v12
	v_mul_f32_e32 v12, 0xbfb8aa3b, v41
	v_exp_f32_e32 v12, v12
	v_mov_b32_e32 v40, v13
	v_add_f32_e32 v12, 1.0, v12
	v_rcp_f32_e32 v43, v12
	s_nop 0
	v_pk_mul_f32 v[12:13], v[40:41], v[42:43]
	s_and_saveexec_b64 s[30:31], s[42:43]
	s_xor_b64 s[30:31], exec, s[30:31]
	v_cvt_pk_bf16_f32 v12, v16, v12
	v_cvt_pk_bf16_f32 v13, v17, v13
	ds_write2_b32 v26, v12, v13 offset1:132
	s_andn2_saveexec_b64 s[30:31], s[30:31]
	v_cvt_pk_bf16_f32 v16, v16, v17
	v_cvt_pk_bf16_f32 v12, v12, v13
	ds_write2_b32 v27, v16, v12 offset1:36
	s_or_b64 exec, exec, s[30:31]
	v_pk_fma_f32 v[14:15], v[0:1], v[14:15], v[8:9]
	v_pk_fma_f32 v[16:17], v[0:1], v[22:23], v[8:9]
	v_pk_fma_f32 v[14:15], v[2:3], v[22:23], v[14:15]
	v_lshlrev_b32_e32 v12, 16, v20
	v_and_b32_e32 v13, 0xffff0000, v20
	v_pk_fma_f32 v[14:15], v[4:5], v[18:19], v[14:15]
	v_pk_fma_f32 v[16:17], v[2:3], v[18:19], v[16:17]
	v_lshlrev_b32_e32 v20, 16, v21
	v_and_b32_e32 v21, 0xffff0000, v21
	v_pk_fma_f32 v[14:15], v[6:7], v[12:13], v[14:15]
	v_pk_fma_f32 v[16:17], v[4:5], v[12:13], v[16:17]
	s_nop 0
	v_pk_fma_f32 v[22:23], v[6:7], v[20:21], v[16:17]
	v_mul_f32_e32 v16, 0xbfb8aa3b, v14
	v_exp_f32_e32 v16, v16
	s_nop 0
	v_add_f32_e32 v16, 1.0, v16
	v_rcp_f32_e32 v16, v16
	s_nop 0
	v_mul_f32_e32 v16, v14, v16
	v_mul_f32_e32 v14, 0xbfb8aa3b, v15
	v_exp_f32_e32 v14, v14
	s_nop 0
	v_add_f32_e32 v14, 1.0, v14
	v_rcp_f32_e32 v40, v14
	v_mul_f32_e32 v14, 0xbfb8aa3b, v22
	v_exp_f32_e32 v14, v14
	s_nop 0
	v_add_f32_e32 v14, 1.0, v14
	v_rcp_f32_e32 v14, v14
	s_nop 0
	v_mul_f32_e32 v17, v22, v14
	v_mul_f32_e32 v14, 0xbfb8aa3b, v23
	v_exp_f32_e32 v14, v14
	v_mov_b32_e32 v22, v15
	v_add_f32_e32 v14, 1.0, v14
	v_rcp_f32_e32 v41, v14
	s_nop 0
	v_pk_mul_f32 v[14:15], v[22:23], v[40:41]
	s_and_saveexec_b64 s[30:31], s[42:43]
	s_xor_b64 s[30:31], exec, s[30:31]
	v_cvt_pk_bf16_f32 v14, v16, v14
	v_cvt_pk_bf16_f32 v15, v17, v15
	v_add_u32_e32 v16, 0x400, v26
	ds_write2_b32 v16, v14, v15 offset0:8 offset1:140
	s_andn2_saveexec_b64 s[30:31], s[30:31]
	v_cvt_pk_bf16_f32 v16, v16, v17
	v_cvt_pk_bf16_f32 v14, v14, v15
	ds_write2_b32 v27, v16, v14 offset0:1 offset1:37
	s_or_b64 exec, exec, s[30:31]
	v_pk_fma_f32 v[18:19], v[0:1], v[18:19], v[8:9]
	v_lshlrev_b32_e32 v14, 16, v38
	v_pk_fma_f32 v[18:19], v[2:3], v[12:13], v[18:19]
	v_and_b32_e32 v15, 0xffff0000, v38
	v_pk_fma_f32 v[18:19], v[4:5], v[20:21], v[18:19]
	v_pk_fma_f32 v[12:13], v[0:1], v[12:13], v[8:9]
	v_pk_fma_f32 v[22:23], v[6:7], v[14:15], v[18:19]
	v_pk_fma_f32 v[12:13], v[2:3], v[20:21], v[12:13]
	v_mul_f32_e32 v19, 0xbfb8aa3b, v23
	v_exp_f32_e32 v19, v19
	v_lshlrev_b32_e32 v16, 16, v39
	v_and_b32_e32 v17, 0xffff0000, v39
	v_pk_fma_f32 v[12:13], v[4:5], v[14:15], v[12:13]
	v_add_f32_e32 v19, 1.0, v19
	v_pk_fma_f32 v[12:13], v[6:7], v[16:17], v[12:13]
	v_rcp_f32_e32 v38, v19
	v_mul_f32_e32 v19, 0xbfb8aa3b, v12
	v_exp_f32_e32 v19, v19
	v_mul_f32_e32 v18, 0xbfb8aa3b, v22
	v_exp_f32_e32 v18, v18
	v_add_f32_e32 v19, 1.0, v19
	v_rcp_f32_e32 v19, v19
	v_add_f32_e32 v18, 1.0, v18
	v_rcp_f32_e32 v18, v18
	v_mul_f32_e32 v19, v12, v19
	v_mul_f32_e32 v12, 0xbfb8aa3b, v13
	v_exp_f32_e32 v12, v12
	v_mul_f32_e32 v18, v22, v18
	v_add_f32_e32 v12, 1.0, v12
	v_rcp_f32_e32 v39, v12
	v_mov_b32_e32 v12, v23
	v_pk_mul_f32 v[12:13], v[12:13], v[38:39]
	s_and_saveexec_b64 s[30:31], s[42:43]
	s_xor_b64 s[30:31], exec, s[30:31]
	v_cvt_pk_bf16_f32 v12, v18, v12
	v_cvt_pk_bf16_f32 v13, v19, v13
	v_add_u32_e32 v18, 0x800, v26
	ds_write2_b32 v18, v12, v13 offset0:16 offset1:148
	s_andn2_saveexec_b64 s[30:31], s[30:31]
	v_cvt_pk_bf16_f32 v18, v18, v19
	v_cvt_pk_bf16_f32 v12, v12, v13
	ds_write2_b32 v27, v18, v12 offset0:2 offset1:38
	s_or_b64 exec, exec, s[30:31]
	v_pk_fma_f32 v[20:21], v[0:1], v[20:21], v[8:9]
	v_lshlrev_b32_e32 v18, 16, v36
	v_pk_fma_f32 v[20:21], v[2:3], v[14:15], v[20:21]
	v_and_b32_e32 v19, 0xffff0000, v36
	v_pk_fma_f32 v[20:21], v[4:5], v[16:17], v[20:21]
	v_pk_fma_f32 v[14:15], v[0:1], v[14:15], v[8:9]
	v_pk_fma_f32 v[22:23], v[6:7], v[18:19], v[20:21]
	v_pk_fma_f32 v[14:15], v[2:3], v[16:17], v[14:15]
	v_mul_f32_e32 v21, 0xbfb8aa3b, v23
	v_exp_f32_e32 v21, v21
	v_lshlrev_b32_e32 v12, 16, v37
	v_and_b32_e32 v13, 0xffff0000, v37
	v_pk_fma_f32 v[14:15], v[4:5], v[18:19], v[14:15]
	v_add_f32_e32 v21, 1.0, v21
	v_pk_fma_f32 v[14:15], v[6:7], v[12:13], v[14:15]
	v_rcp_f32_e32 v36, v21
	v_mul_f32_e32 v21, 0xbfb8aa3b, v14
	v_exp_f32_e32 v21, v21
	v_mul_f32_e32 v20, 0xbfb8aa3b, v22
	v_exp_f32_e32 v20, v20
	v_add_f32_e32 v21, 1.0, v21
	v_rcp_f32_e32 v21, v21
	v_add_f32_e32 v20, 1.0, v20
	v_rcp_f32_e32 v20, v20
	v_mul_f32_e32 v21, v14, v21
	v_mul_f32_e32 v14, 0xbfb8aa3b, v15
	v_exp_f32_e32 v14, v14
	v_mul_f32_e32 v20, v22, v20
	v_add_f32_e32 v14, 1.0, v14
	v_rcp_f32_e32 v37, v14
	v_mov_b32_e32 v14, v23
	v_pk_mul_f32 v[14:15], v[14:15], v[36:37]
	s_and_saveexec_b64 s[30:31], s[42:43]
	s_xor_b64 s[30:31], exec, s[30:31]
	v_cvt_pk_bf16_f32 v14, v20, v14
	v_cvt_pk_bf16_f32 v15, v21, v15
	v_add_u32_e32 v20, 0xc00, v26
	ds_write2_b32 v20, v14, v15 offset0:24 offset1:156
	s_andn2_saveexec_b64 s[30:31], s[30:31]
	v_cvt_pk_bf16_f32 v20, v20, v21
	v_cvt_pk_bf16_f32 v14, v14, v15
	ds_write2_b32 v27, v20, v14 offset0:3 offset1:39
	s_or_b64 exec, exec, s[30:31]
	v_pk_fma_f32 v[16:17], v[0:1], v[16:17], v[8:9]
	v_lshlrev_b32_e32 v20, 16, v34
	v_pk_fma_f32 v[16:17], v[2:3], v[18:19], v[16:17]
	v_pk_fma_f32 v[18:19], v[0:1], v[18:19], v[8:9]
	v_and_b32_e32 v21, 0xffff0000, v34
	v_pk_fma_f32 v[16:17], v[4:5], v[12:13], v[16:17]
	v_pk_fma_f32 v[18:19], v[2:3], v[12:13], v[18:19]
	v_lshlrev_b32_e32 v14, 16, v35
	v_and_b32_e32 v15, 0xffff0000, v35
	v_pk_fma_f32 v[16:17], v[6:7], v[20:21], v[16:17]
	v_pk_fma_f32 v[18:19], v[4:5], v[20:21], v[18:19]
	s_nop 0
	v_pk_fma_f32 v[22:23], v[6:7], v[14:15], v[18:19]
	v_mul_f32_e32 v18, 0xbfb8aa3b, v16
	v_exp_f32_e32 v18, v18
	s_nop 0
	v_add_f32_e32 v18, 1.0, v18
	v_rcp_f32_e32 v18, v18
	s_nop 0
	v_mul_f32_e32 v18, v16, v18
	v_mul_f32_e32 v16, 0xbfb8aa3b, v17
	v_exp_f32_e32 v16, v16
	s_nop 0
	v_add_f32_e32 v16, 1.0, v16
	v_rcp_f32_e32 v34, v16
	v_mul_f32_e32 v16, 0xbfb8aa3b, v22
	v_exp_f32_e32 v16, v16
	s_nop 0
	v_add_f32_e32 v16, 1.0, v16
	v_rcp_f32_e32 v16, v16
	s_nop 0
	v_mul_f32_e32 v19, v22, v16
	v_mul_f32_e32 v16, 0xbfb8aa3b, v23
	v_exp_f32_e32 v16, v16
	v_mov_b32_e32 v22, v17
	v_add_f32_e32 v16, 1.0, v16
	v_rcp_f32_e32 v35, v16
	s_nop 0
	v_pk_mul_f32 v[16:17], v[22:23], v[34:35]
	s_and_saveexec_b64 s[30:31], s[42:43]
	s_xor_b64 s[30:31], exec, s[30:31]
	v_cvt_pk_bf16_f32 v16, v18, v16
	v_cvt_pk_bf16_f32 v17, v19, v17
	v_add_u32_e32 v18, 0x1000, v26
	ds_write2_b32 v18, v16, v17 offset0:32 offset1:164
	s_andn2_saveexec_b64 s[30:31], s[30:31]
	v_cvt_pk_bf16_f32 v18, v18, v19
	v_cvt_pk_bf16_f32 v16, v16, v17
	ds_write2_b32 v27, v18, v16 offset0:4 offset1:40
	s_or_b64 exec, exec, s[30:31]
	v_pk_fma_f32 v[12:13], v[0:1], v[12:13], v[8:9]
	v_lshlrev_b32_e32 v16, 16, v32
	v_pk_fma_f32 v[12:13], v[2:3], v[20:21], v[12:13]
	v_pk_fma_f32 v[20:21], v[0:1], v[20:21], v[8:9]
	v_and_b32_e32 v17, 0xffff0000, v32
	v_pk_fma_f32 v[12:13], v[4:5], v[14:15], v[12:13]
	v_pk_fma_f32 v[20:21], v[2:3], v[14:15], v[20:21]
	v_lshlrev_b32_e32 v18, 16, v33
	v_and_b32_e32 v19, 0xffff0000, v33
	v_pk_fma_f32 v[12:13], v[6:7], v[16:17], v[12:13]
	v_pk_fma_f32 v[20:21], v[4:5], v[16:17], v[20:21]
	s_nop 0
	v_pk_fma_f32 v[22:23], v[6:7], v[18:19], v[20:21]
	v_mul_f32_e32 v20, 0xbfb8aa3b, v12
	v_exp_f32_e32 v20, v20
	s_nop 0
	v_add_f32_e32 v20, 1.0, v20
	v_rcp_f32_e32 v20, v20
	s_nop 0
	v_mul_f32_e32 v20, v12, v20
	v_mul_f32_e32 v12, 0xbfb8aa3b, v13
	v_exp_f32_e32 v12, v12
	s_nop 0
	v_add_f32_e32 v12, 1.0, v12
	v_rcp_f32_e32 v32, v12
	v_mul_f32_e32 v12, 0xbfb8aa3b, v22
	v_exp_f32_e32 v12, v12
	s_nop 0
	v_add_f32_e32 v12, 1.0, v12
	v_rcp_f32_e32 v12, v12
	s_nop 0
	v_mul_f32_e32 v21, v22, v12
	v_mul_f32_e32 v12, 0xbfb8aa3b, v23
	v_exp_f32_e32 v12, v12
	v_mov_b32_e32 v22, v13
	v_add_f32_e32 v12, 1.0, v12
	v_rcp_f32_e32 v33, v12
	s_nop 0
	v_pk_mul_f32 v[12:13], v[22:23], v[32:33]
	s_and_saveexec_b64 s[30:31], s[42:43]
	s_xor_b64 s[30:31], exec, s[30:31]
	v_cvt_pk_bf16_f32 v12, v20, v12
	v_cvt_pk_bf16_f32 v13, v21, v13
	v_add_u32_e32 v20, 0x1400, v26
	ds_write2_b32 v20, v12, v13 offset0:40 offset1:172
	s_andn2_saveexec_b64 s[30:31], s[30:31]
	v_cvt_pk_bf16_f32 v20, v20, v21
	v_cvt_pk_bf16_f32 v12, v12, v13
	ds_write2_b32 v27, v20, v12 offset0:5 offset1:41
	s_or_b64 exec, exec, s[30:31]
	v_pk_fma_f32 v[14:15], v[0:1], v[14:15], v[8:9]
	v_lshlrev_b32_e32 v20, 16, v30
	v_pk_fma_f32 v[14:15], v[2:3], v[16:17], v[14:15]
	v_pk_fma_f32 v[16:17], v[0:1], v[16:17], v[8:9]
	v_and_b32_e32 v21, 0xffff0000, v30
	v_pk_fma_f32 v[14:15], v[4:5], v[18:19], v[14:15]
	v_pk_fma_f32 v[16:17], v[2:3], v[18:19], v[16:17]
	v_lshlrev_b32_e32 v12, 16, v31
	v_and_b32_e32 v13, 0xffff0000, v31
	v_pk_fma_f32 v[14:15], v[6:7], v[20:21], v[14:15]
	v_pk_fma_f32 v[16:17], v[4:5], v[20:21], v[16:17]
	s_nop 0
	v_pk_fma_f32 v[22:23], v[6:7], v[12:13], v[16:17]
	v_mul_f32_e32 v16, 0xbfb8aa3b, v14
	v_exp_f32_e32 v16, v16
	s_nop 0
	v_add_f32_e32 v16, 1.0, v16
	v_rcp_f32_e32 v16, v16
	s_nop 0
	v_mul_f32_e32 v16, v14, v16
	v_mul_f32_e32 v14, 0xbfb8aa3b, v15
	v_exp_f32_e32 v14, v14
	s_nop 0
	v_add_f32_e32 v14, 1.0, v14
	v_rcp_f32_e32 v30, v14
	v_mul_f32_e32 v14, 0xbfb8aa3b, v22
	v_exp_f32_e32 v14, v14
	s_nop 0
	v_add_f32_e32 v14, 1.0, v14
	v_rcp_f32_e32 v14, v14
	s_nop 0
	v_mul_f32_e32 v17, v22, v14
	v_mul_f32_e32 v14, 0xbfb8aa3b, v23
	v_exp_f32_e32 v14, v14
	v_mov_b32_e32 v22, v15
	v_add_f32_e32 v14, 1.0, v14
	v_rcp_f32_e32 v31, v14
	s_nop 0
	v_pk_mul_f32 v[14:15], v[22:23], v[30:31]
	s_and_saveexec_b64 s[30:31], s[42:43]
	s_xor_b64 s[30:31], exec, s[30:31]
	v_cvt_pk_bf16_f32 v14, v16, v14
	v_cvt_pk_bf16_f32 v15, v17, v15
	v_add_u32_e32 v16, 0x1800, v26
	ds_write2_b32 v16, v14, v15 offset0:48 offset1:180
	s_andn2_saveexec_b64 s[30:31], s[30:31]
	v_cvt_pk_bf16_f32 v16, v16, v17
	v_cvt_pk_bf16_f32 v14, v14, v15
	ds_write2_b32 v27, v16, v14 offset0:6 offset1:42
	s_or_b64 exec, exec, s[30:31]
	v_pk_fma_f32 v[18:19], v[0:1], v[18:19], v[8:9]
	v_lshlrev_b32_e32 v16, 16, v29
	v_pk_fma_f32 v[18:19], v[2:3], v[20:21], v[18:19]
	v_pk_fma_f32 v[20:21], v[0:1], v[20:21], v[8:9]
	v_and_b32_e32 v17, 0xffff0000, v29
	v_pk_fma_f32 v[18:19], v[4:5], v[12:13], v[18:19]
	v_pk_fma_f32 v[20:21], v[2:3], v[12:13], v[20:21]
	v_lshlrev_b32_e32 v14, 16, v28
	v_and_b32_e32 v15, 0xffff0000, v28
	v_pk_fma_f32 v[18:19], v[6:7], v[16:17], v[18:19]
	v_pk_fma_f32 v[20:21], v[4:5], v[16:17], v[20:21]
	s_nop 0
	v_pk_fma_f32 v[22:23], v[6:7], v[14:15], v[20:21]
	v_mul_f32_e32 v20, 0xbfb8aa3b, v18
	v_exp_f32_e32 v20, v20
	s_nop 0
	v_add_f32_e32 v20, 1.0, v20
	v_rcp_f32_e32 v20, v20
	s_nop 0
	v_mul_f32_e32 v20, v18, v20
	v_mul_f32_e32 v18, 0xbfb8aa3b, v19
	v_exp_f32_e32 v18, v18
	s_nop 0
	v_add_f32_e32 v18, 1.0, v18
	v_rcp_f32_e32 v28, v18
	v_mul_f32_e32 v18, 0xbfb8aa3b, v22
	v_exp_f32_e32 v18, v18
	s_nop 0
	v_add_f32_e32 v18, 1.0, v18
	v_rcp_f32_e32 v18, v18
	s_nop 0
	v_mul_f32_e32 v21, v22, v18
	v_mul_f32_e32 v18, 0xbfb8aa3b, v23
	v_exp_f32_e32 v18, v18
	v_mov_b32_e32 v22, v19
	v_add_f32_e32 v18, 1.0, v18
	v_rcp_f32_e32 v29, v18
	s_nop 0
	v_pk_mul_f32 v[18:19], v[22:23], v[28:29]
	s_and_saveexec_b64 s[30:31], s[42:43]
	s_xor_b64 s[30:31], exec, s[30:31]
	v_cvt_pk_bf16_f32 v18, v20, v18
	v_cvt_pk_bf16_f32 v19, v21, v19
	v_add_u32_e32 v20, 0x1c00, v26
	ds_write2_b32 v20, v18, v19 offset0:56 offset1:188
	s_andn2_saveexec_b64 s[30:31], s[30:31]
	s_cbranch_execz .LBB0_346
	v_cvt_pk_bf16_f32 v20, v20, v21
	v_cvt_pk_bf16_f32 v18, v18, v19
	ds_write2_b32 v27, v20, v18 offset0:7 offset1:43
	s_branch .LBB0_346

.LBB0_398:
	v_lshlrev_b32_e32 v19, 3, v37
	v_and_b32_e32 v19, 0xffffff00, v19
	s_add_i32 s31, 0, 0x1000
	s_mul_i32 s30, s71, 0x1600
	s_movk_i32 s0, 0x120
	v_add_u32_e32 v24, s31, v19
	s_add_i32 s31, 0, 0x2000
	s_mul_hi_i32 s25, s71, 0x1600
	v_mul_lo_u32 v18, v37, s0
	s_add_u32 s30, s15, s30
	v_add_u32_e32 v25, s31, v18
	s_addc_u32 s31, s70, s25
	v_cmp_gt_i32_e64 s[40:41], s2, v37
	v_lshl_add_u64 v[10:11], v[10:11], 1, s[30:31]
	s_mov_b32 s25, -16
	s_mov_b32 s100, 0xfffeb600
	s_mov_b32 s101, -1
	v_lshl_add_u64 v[114:115], v[10:11], 0, s[100:101]
	s_mov_b32 s100, 0x1600
	s_mov_b32 s101, 0
	global_load_dword v44, v[114:115], off
	v_lshl_add_u64 v[114:115], v[114:115], 0, s[100:101]
	global_load_dword v45, v[114:115], off
	v_lshl_add_u64 v[114:115], v[114:115], 0, s[100:101]
	global_load_dword v46, v[114:115], off
	v_lshl_add_u64 v[114:115], v[114:115], 0, s[100:101]
	global_load_dword v47, v[114:115], off
	v_lshl_add_u64 v[114:115], v[114:115], 0, s[100:101]
	global_load_dword v48, v[114:115], off
	v_lshl_add_u64 v[114:115], v[114:115], 0, s[100:101]
	global_load_dword v49, v[114:115], off
	v_lshl_add_u64 v[114:115], v[114:115], 0, s[100:101]
	global_load_dword v50, v[114:115], off
	v_lshl_add_u64 v[114:115], v[114:115], 0, s[100:101]
	global_load_dword v51, v[114:115], off
	v_lshl_add_u64 v[114:115], v[114:115], 0, s[100:101]
	global_load_dword v52, v[114:115], off
	v_lshl_add_u64 v[114:115], v[114:115], 0, s[100:101]
	global_load_dword v53, v[114:115], off
	v_lshl_add_u64 v[114:115], v[114:115], 0, s[100:101]
	global_load_dword v54, v[114:115], off
	v_lshl_add_u64 v[114:115], v[114:115], 0, s[100:101]
	global_load_dword v55, v[114:115], off
	v_lshl_add_u64 v[114:115], v[114:115], 0, s[100:101]
	global_load_dword v56, v[114:115], off
	v_lshl_add_u64 v[114:115], v[114:115], 0, s[100:101]
	global_load_dword v57, v[114:115], off
	v_lshl_add_u64 v[114:115], v[114:115], 0, s[100:101]
	global_load_dword v58, v[114:115], off
	v_lshl_add_u64 v[114:115], v[114:115], 0, s[100:101]
	global_load_dword v59, v[114:115], off
	s_branch .LBB0_400

.LBB0_400:
	s_waitcnt vmcnt(0) lgkmcnt(0)
	v_mov_b32_e32 v23, v44
	v_mov_b32_e32 v42, v45
	v_mov_b32_e32 v18, v46
	v_mov_b32_e32 v19, v47
	v_mov_b32_e32 v40, v48
	v_mov_b32_e32 v41, v49
	v_mov_b32_e32 v38, v50
	v_mov_b32_e32 v39, v51
	v_mov_b32_e32 v34, v52
	v_mov_b32_e32 v35, v53
	v_mov_b32_e32 v30, v54
	v_mov_b32_e32 v31, v55
	v_mov_b32_e32 v28, v56
	v_mov_b32_e32 v29, v57
	v_mov_b32_e32 v27, v58
	v_mov_b32_e32 v26, v59
	s_cmp_ge_i32 s25, 32
	s_cbranch_scc1 .Lmy_cp400_nl
	s_mov_b32 s100, 0x1600
	s_mov_b32 s101, 0
	v_lshl_add_u64 v[114:115], v[10:11], 0, s[100:101]
	global_load_dword v44, v[114:115], off
	v_lshl_add_u64 v[114:115], v[114:115], 0, s[100:101]
	global_load_dword v45, v[114:115], off
	v_lshl_add_u64 v[114:115], v[114:115], 0, s[100:101]
	global_load_dword v46, v[114:115], off
	v_lshl_add_u64 v[114:115], v[114:115], 0, s[100:101]
	global_load_dword v47, v[114:115], off
	v_lshl_add_u64 v[114:115], v[114:115], 0, s[100:101]
	global_load_dword v48, v[114:115], off
	v_lshl_add_u64 v[114:115], v[114:115], 0, s[100:101]
	global_load_dword v49, v[114:115], off
	v_lshl_add_u64 v[114:115], v[114:115], 0, s[100:101]
	global_load_dword v50, v[114:115], off
	v_lshl_add_u64 v[114:115], v[114:115], 0, s[100:101]
	global_load_dword v51, v[114:115], off
	v_lshl_add_u64 v[114:115], v[114:115], 0, s[100:101]
	global_load_dword v52, v[114:115], off
	v_lshl_add_u64 v[114:115], v[114:115], 0, s[100:101]
	global_load_dword v53, v[114:115], off
	v_lshl_add_u64 v[114:115], v[114:115], 0, s[100:101]
	global_load_dword v54, v[114:115], off
	v_lshl_add_u64 v[114:115], v[114:115], 0, s[100:101]
	global_load_dword v55, v[114:115], off
	v_lshl_add_u64 v[114:115], v[114:115], 0, s[100:101]
	global_load_dword v56, v[114:115], off
	v_lshl_add_u64 v[114:115], v[114:115], 0, s[100:101]
	global_load_dword v57, v[114:115], off
	v_lshl_add_u64 v[114:115], v[114:115], 0, s[100:101]
	global_load_dword v58, v[114:115], off
	v_lshl_add_u64 v[114:115], v[114:115], 0, s[100:101]
	global_load_dword v59, v[114:115], off
.Lmy_cp400_nl:
	v_pk_fma_f32 v[12:13], v[0:1], v[12:13], v[8:9]
	v_pk_fma_f32 v[12:13], v[2:3], v[16:17], v[12:13]
	s_nop 0
	v_pk_fma_f32 v[12:13], v[4:5], v[14:15], v[12:13]
	s_nop 0
	s_nop 0
	v_pk_fma_f32 v[16:17], v[0:1], v[16:17], v[8:9]
	s_nop 0
	v_pk_fma_f32 v[16:17], v[2:3], v[14:15], v[16:17]
	s_nop 0
	v_lshlrev_b32_e32 v22, 16, v23
	v_and_b32_e32 v23, 0xffff0000, v23
	s_nop 0
	v_pk_fma_f32 v[12:13], v[6:7], v[22:23], v[12:13]
	s_nop 0
	v_mul_f32_e32 v43, 0xbfb8aa3b, v13
	s_nop 0
	v_exp_f32_e32 v43, v43
	s_nop 0
	v_add_f32_e32 v43, 1.0, v43
	s_nop 0
	v_rcp_f32_e32 v43, v43
	s_nop 0
	v_pk_fma_f32 v[16:17], v[4:5], v[22:23], v[16:17]
	s_nop 0
	s_nop 1
	v_lshlrev_b32_e32 v20, 16, v42
	v_and_b32_e32 v21, 0xffff0000, v42
	v_mul_f32_e32 v42, 0xbfb8aa3b, v12
	v_exp_f32_e32 v42, v42
	v_pk_fma_f32 v[16:17], v[6:7], v[20:21], v[16:17]
	v_add_f32_e32 v42, 1.0, v42
	v_rcp_f32_e32 v42, v42
	s_nop 0
	v_pk_mul_f32 v[12:13], v[12:13], v[42:43]
	v_mul_f32_e32 v42, 0xbfb8aa3b, v16
	v_mul_f32_e32 v43, 0xbfb8aa3b, v17
	v_exp_f32_e32 v42, v42
	v_exp_f32_e32 v43, v43
	v_add_f32_e32 v42, 1.0, v42
	v_add_f32_e32 v43, 1.0, v43
	v_rcp_f32_e32 v42, v42
	v_rcp_f32_e32 v43, v43
	s_nop 0
	v_pk_mul_f32 v[16:17], v[16:17], v[42:43]
	s_and_saveexec_b64 s[30:31], s[40:41]
	s_cbranch_execz .LBB0_402
	ds_read_b64 v[42:43], v24
	s_waitcnt lgkmcnt(0)
	v_pk_mul_f32 v[12:13], v[12:13], v[42:43] op_sel_hi:[1,0]
	v_pk_mul_f32 v[16:17], v[16:17], v[42:43] op_sel:[0,1]
.LBB0_402:
	s_or_b64 exec, exec, s[30:31]
	v_pk_fma_f32 v[14:15], v[0:1], v[14:15], v[8:9]
	v_cvt_pk_bf16_f32 v12, v12, v16
	v_cvt_pk_bf16_f32 v13, v13, v17
	v_pk_fma_f32 v[14:15], v[2:3], v[22:23], v[14:15]
	ds_write2_b32 v25, v12, v13 offset1:36
	v_lshlrev_b32_e32 v12, 16, v18
	v_and_b32_e32 v13, 0xffff0000, v18
	v_pk_fma_f32 v[14:15], v[4:5], v[20:21], v[14:15]
	v_pk_fma_f32 v[16:17], v[0:1], v[22:23], v[8:9]
	v_pk_fma_f32 v[14:15], v[6:7], v[12:13], v[14:15]
	v_pk_fma_f32 v[16:17], v[2:3], v[20:21], v[16:17]
	v_mul_f32_e32 v22, 0xbfb8aa3b, v14
	v_mul_f32_e32 v23, 0xbfb8aa3b, v15
	v_exp_f32_e32 v22, v22
	v_exp_f32_e32 v23, v23
	v_lshlrev_b32_e32 v18, 16, v19
	v_and_b32_e32 v19, 0xffff0000, v19
	v_add_f32_e32 v22, 1.0, v22
	v_add_f32_e32 v23, 1.0, v23
	v_rcp_f32_e32 v22, v22
	v_rcp_f32_e32 v23, v23
	v_pk_fma_f32 v[16:17], v[4:5], v[12:13], v[16:17]
	v_pk_mul_f32 v[14:15], v[14:15], v[22:23]
	v_pk_fma_f32 v[16:17], v[6:7], v[18:19], v[16:17]
	s_nop 0
	v_mul_f32_e32 v22, 0xbfb8aa3b, v16
	v_mul_f32_e32 v23, 0xbfb8aa3b, v17
	v_exp_f32_e32 v22, v22
	v_exp_f32_e32 v23, v23
	v_add_f32_e32 v22, 1.0, v22
	v_add_f32_e32 v23, 1.0, v23
	v_rcp_f32_e32 v22, v22
	v_rcp_f32_e32 v23, v23
	s_nop 0
	v_pk_mul_f32 v[16:17], v[16:17], v[22:23]
	s_and_saveexec_b64 s[30:31], s[40:41]
	s_cbranch_execz .LBB0_404
	ds_read_b64 v[22:23], v24 offset:8
	s_waitcnt lgkmcnt(0)
	v_pk_mul_f32 v[14:15], v[14:15], v[22:23] op_sel_hi:[1,0]
	v_pk_mul_f32 v[16:17], v[16:17], v[22:23] op_sel:[0,1]
.LBB0_404:
	s_or_b64 exec, exec, s[30:31]
	v_pk_fma_f32 v[20:21], v[0:1], v[20:21], v[8:9]
	v_cvt_pk_bf16_f32 v14, v14, v16
	v_cvt_pk_bf16_f32 v15, v15, v17
	v_pk_fma_f32 v[20:21], v[2:3], v[12:13], v[20:21]
	v_pk_fma_f32 v[12:13], v[0:1], v[12:13], v[8:9]
	ds_write2_b32 v25, v14, v15 offset0:1 offset1:37
	v_lshlrev_b32_e32 v14, 16, v40
	v_and_b32_e32 v15, 0xffff0000, v40
	v_pk_fma_f32 v[20:21], v[4:5], v[18:19], v[20:21]
	v_pk_fma_f32 v[12:13], v[2:3], v[18:19], v[12:13]
	v_lshlrev_b32_e32 v16, 16, v41
	v_and_b32_e32 v17, 0xffff0000, v41
	v_pk_fma_f32 v[20:21], v[6:7], v[14:15], v[20:21]
	v_pk_fma_f32 v[12:13], v[4:5], v[14:15], v[12:13]
	s_nop 0
	v_pk_fma_f32 v[22:23], v[6:7], v[16:17], v[12:13]
	v_mul_f32_e32 v12, 0xbfb8aa3b, v20
	v_mul_f32_e32 v13, 0xbfb8aa3b, v21
	v_exp_f32_e32 v12, v12
	v_exp_f32_e32 v13, v13
	v_add_f32_e32 v12, 1.0, v12
	v_add_f32_e32 v13, 1.0, v13
	v_rcp_f32_e32 v12, v12
	v_rcp_f32_e32 v13, v13
	s_nop 0
	v_pk_mul_f32 v[12:13], v[20:21], v[12:13]
	v_mul_f32_e32 v20, 0xbfb8aa3b, v22
	v_mul_f32_e32 v21, 0xbfb8aa3b, v23
	v_exp_f32_e32 v20, v20
	v_exp_f32_e32 v21, v21
	v_add_f32_e32 v20, 1.0, v20
	v_add_f32_e32 v21, 1.0, v21
	v_rcp_f32_e32 v20, v20
	v_rcp_f32_e32 v21, v21
	s_nop 0
	v_pk_mul_f32 v[20:21], v[22:23], v[20:21]
	s_and_saveexec_b64 s[30:31], s[40:41]
	s_cbranch_execz .LBB0_406
	ds_read_b64 v[22:23], v24 offset:16
	s_waitcnt lgkmcnt(0)
	v_pk_mul_f32 v[12:13], v[12:13], v[22:23] op_sel_hi:[1,0]
	v_pk_mul_f32 v[20:21], v[20:21], v[22:23] op_sel:[0,1]
.LBB0_406:
	s_or_b64 exec, exec, s[30:31]
	v_pk_fma_f32 v[18:19], v[0:1], v[18:19], v[8:9]
	v_cvt_pk_bf16_f32 v12, v12, v20
	v_pk_fma_f32 v[18:19], v[2:3], v[14:15], v[18:19]
	v_pk_fma_f32 v[14:15], v[0:1], v[14:15], v[8:9]
	v_cvt_pk_bf16_f32 v13, v13, v21
	v_lshlrev_b32_e32 v22, 16, v38
	v_and_b32_e32 v23, 0xffff0000, v38
	v_pk_fma_f32 v[18:19], v[4:5], v[16:17], v[18:19]
	v_pk_fma_f32 v[14:15], v[2:3], v[16:17], v[14:15]
	ds_write2_b32 v25, v12, v13 offset0:2 offset1:38
	v_lshlrev_b32_e32 v12, 16, v39
	v_and_b32_e32 v13, 0xffff0000, v39
	v_pk_fma_f32 v[18:19], v[6:7], v[22:23], v[18:19]
	v_pk_fma_f32 v[14:15], v[4:5], v[22:23], v[14:15]
	s_nop 0
	v_pk_fma_f32 v[20:21], v[6:7], v[12:13], v[14:15]
	v_mul_f32_e32 v14, 0xbfb8aa3b, v18
	v_mul_f32_e32 v15, 0xbfb8aa3b, v19
	v_exp_f32_e32 v14, v14
	v_exp_f32_e32 v15, v15
	v_add_f32_e32 v14, 1.0, v14
	v_add_f32_e32 v15, 1.0, v15
	v_rcp_f32_e32 v14, v14
	v_rcp_f32_e32 v15, v15
	s_nop 0
	v_pk_mul_f32 v[14:15], v[18:19], v[14:15]
	v_mul_f32_e32 v18, 0xbfb8aa3b, v20
	v_mul_f32_e32 v19, 0xbfb8aa3b, v21
	v_exp_f32_e32 v18, v18
	v_exp_f32_e32 v19, v19
	v_add_f32_e32 v18, 1.0, v18
	v_add_f32_e32 v19, 1.0, v19
	v_rcp_f32_e32 v18, v18
	v_rcp_f32_e32 v19, v19
	s_nop 0
	v_pk_mul_f32 v[18:19], v[20:21], v[18:19]
	s_and_saveexec_b64 s[30:31], s[40:41]
	s_cbranch_execz .LBB0_408
	ds_read_b64 v[20:21], v24 offset:24
	s_waitcnt lgkmcnt(0)
	v_pk_mul_f32 v[14:15], v[14:15], v[20:21] op_sel_hi:[1,0]
	v_pk_mul_f32 v[18:19], v[18:19], v[20:21] op_sel:[0,1]
.LBB0_408:
	s_or_b64 exec, exec, s[30:31]
	v_pk_fma_f32 v[16:17], v[0:1], v[16:17], v[8:9]
	v_lshlrev_b32_e32 v20, 16, v34
	v_pk_fma_f32 v[16:17], v[2:3], v[22:23], v[16:17]
	v_and_b32_e32 v21, 0xffff0000, v34
	v_pk_fma_f32 v[16:17], v[4:5], v[12:13], v[16:17]
	v_cvt_pk_bf16_f32 v14, v14, v18
	v_pk_fma_f32 v[16:17], v[6:7], v[20:21], v[16:17]
	v_cvt_pk_bf16_f32 v15, v15, v19
	v_pk_fma_f32 v[18:19], v[0:1], v[22:23], v[8:9]
	v_mul_f32_e32 v22, 0xbfb8aa3b, v16
	v_mul_f32_e32 v23, 0xbfb8aa3b, v17
	v_exp_f32_e32 v22, v22
	v_exp_f32_e32 v23, v23
	v_pk_fma_f32 v[18:19], v[2:3], v[12:13], v[18:19]
	ds_write2_b32 v25, v14, v15 offset0:3 offset1:39
	v_add_f32_e32 v22, 1.0, v22
	v_add_f32_e32 v23, 1.0, v23
	v_rcp_f32_e32 v22, v22
	v_rcp_f32_e32 v23, v23
	v_lshlrev_b32_e32 v14, 16, v35
	v_and_b32_e32 v15, 0xffff0000, v35
	v_pk_fma_f32 v[18:19], v[4:5], v[20:21], v[18:19]
	v_pk_mul_f32 v[16:17], v[16:17], v[22:23]
	v_pk_fma_f32 v[18:19], v[6:7], v[14:15], v[18:19]
	s_nop 0
	v_mul_f32_e32 v22, 0xbfb8aa3b, v18
	v_mul_f32_e32 v23, 0xbfb8aa3b, v19
	v_exp_f32_e32 v22, v22
	v_exp_f32_e32 v23, v23
	v_add_f32_e32 v22, 1.0, v22
	v_add_f32_e32 v23, 1.0, v23
	v_rcp_f32_e32 v22, v22
	v_rcp_f32_e32 v23, v23
	s_nop 0
	v_pk_mul_f32 v[18:19], v[18:19], v[22:23]
	s_and_saveexec_b64 s[30:31], s[40:41]
	s_cbranch_execz .LBB0_410
	ds_read_b64 v[22:23], v24 offset:32
	s_waitcnt lgkmcnt(0)
	v_pk_mul_f32 v[16:17], v[16:17], v[22:23] op_sel_hi:[1,0]
	v_pk_mul_f32 v[18:19], v[18:19], v[22:23] op_sel:[0,1]
.LBB0_410:
	s_or_b64 exec, exec, s[30:31]
	v_pk_fma_f32 v[12:13], v[0:1], v[12:13], v[8:9]
	v_cvt_pk_bf16_f32 v16, v16, v18
	v_cvt_pk_bf16_f32 v17, v17, v19
	v_pk_fma_f32 v[12:13], v[2:3], v[20:21], v[12:13]
	ds_write2_b32 v25, v16, v17 offset0:4 offset1:40
	v_lshlrev_b32_e32 v16, 16, v30
	v_and_b32_e32 v17, 0xffff0000, v30
	v_pk_fma_f32 v[12:13], v[4:5], v[14:15], v[12:13]
	v_pk_fma_f32 v[20:21], v[0:1], v[20:21], v[8:9]
	v_pk_fma_f32 v[12:13], v[6:7], v[16:17], v[12:13]
	v_pk_fma_f32 v[20:21], v[2:3], v[14:15], v[20:21]
	v_mul_f32_e32 v22, 0xbfb8aa3b, v12
	v_mul_f32_e32 v23, 0xbfb8aa3b, v13
	v_exp_f32_e32 v22, v22
	v_exp_f32_e32 v23, v23
	v_lshlrev_b32_e32 v18, 16, v31
	v_and_b32_e32 v19, 0xffff0000, v31
	v_add_f32_e32 v22, 1.0, v22
	v_add_f32_e32 v23, 1.0, v23
	v_rcp_f32_e32 v22, v22
	v_rcp_f32_e32 v23, v23
	v_pk_fma_f32 v[20:21], v[4:5], v[16:17], v[20:21]
	v_pk_mul_f32 v[12:13], v[12:13], v[22:23]
	v_pk_fma_f32 v[20:21], v[6:7], v[18:19], v[20:21]
	s_nop 0
	v_mul_f32_e32 v22, 0xbfb8aa3b, v20
	v_mul_f32_e32 v23, 0xbfb8aa3b, v21
	v_exp_f32_e32 v22, v22
	v_exp_f32_e32 v23, v23
	v_add_f32_e32 v22, 1.0, v22
	v_add_f32_e32 v23, 1.0, v23
	v_rcp_f32_e32 v22, v22
	v_rcp_f32_e32 v23, v23
	s_nop 0
	v_pk_mul_f32 v[20:21], v[20:21], v[22:23]
	s_and_saveexec_b64 s[30:31], s[40:41]
	s_cbranch_execz .LBB0_412
	ds_read_b64 v[22:23], v24 offset:40
	s_waitcnt lgkmcnt(0)
	v_pk_mul_f32 v[12:13], v[12:13], v[22:23] op_sel_hi:[1,0]
	v_pk_mul_f32 v[20:21], v[20:21], v[22:23] op_sel:[0,1]
.LBB0_412:
	s_or_b64 exec, exec, s[30:31]
	v_pk_fma_f32 v[14:15], v[0:1], v[14:15], v[8:9]
	v_cvt_pk_bf16_f32 v12, v12, v20
	v_pk_fma_f32 v[14:15], v[2:3], v[16:17], v[14:15]
	v_cvt_pk_bf16_f32 v13, v13, v21
	v_lshlrev_b32_e32 v20, 16, v28
	v_and_b32_e32 v21, 0xffff0000, v28
	v_pk_fma_f32 v[14:15], v[4:5], v[18:19], v[14:15]
	v_pk_fma_f32 v[16:17], v[0:1], v[16:17], v[8:9]
	v_pk_fma_f32 v[14:15], v[6:7], v[20:21], v[14:15]
	v_pk_fma_f32 v[16:17], v[2:3], v[18:19], v[16:17]
	v_mul_f32_e32 v22, 0xbfb8aa3b, v14
	v_mul_f32_e32 v23, 0xbfb8aa3b, v15
	v_exp_f32_e32 v22, v22
	v_exp_f32_e32 v23, v23
	ds_write2_b32 v25, v12, v13 offset0:5 offset1:41
	v_lshlrev_b32_e32 v12, 16, v29
	v_add_f32_e32 v22, 1.0, v22
	v_add_f32_e32 v23, 1.0, v23
	v_rcp_f32_e32 v22, v22
	v_rcp_f32_e32 v23, v23
	v_and_b32_e32 v13, 0xffff0000, v29
	v_pk_fma_f32 v[16:17], v[4:5], v[20:21], v[16:17]
	v_pk_mul_f32 v[14:15], v[14:15], v[22:23]
	v_pk_fma_f32 v[16:17], v[6:7], v[12:13], v[16:17]
	s_nop 0
	v_mul_f32_e32 v22, 0xbfb8aa3b, v16
	v_mul_f32_e32 v23, 0xbfb8aa3b, v17
	v_exp_f32_e32 v22, v22
	v_exp_f32_e32 v23, v23
	v_add_f32_e32 v22, 1.0, v22
	v_add_f32_e32 v23, 1.0, v23
	v_rcp_f32_e32 v22, v22
	v_rcp_f32_e32 v23, v23
	s_nop 0
	v_pk_mul_f32 v[16:17], v[16:17], v[22:23]
	s_and_saveexec_b64 s[30:31], s[40:41]
	s_cbranch_execz .LBB0_414
	ds_read_b64 v[22:23], v24 offset:48
	s_waitcnt lgkmcnt(0)
	v_pk_mul_f32 v[14:15], v[14:15], v[22:23] op_sel_hi:[1,0]
	v_pk_mul_f32 v[16:17], v[16:17], v[22:23] op_sel:[0,1]
.LBB0_414:
	s_or_b64 exec, exec, s[30:31]
	v_pk_fma_f32 v[18:19], v[0:1], v[18:19], v[8:9]
	v_cvt_pk_bf16_f32 v14, v14, v16
	v_pk_fma_f32 v[18:19], v[2:3], v[20:21], v[18:19]
	v_cvt_pk_bf16_f32 v15, v15, v17
	v_lshlrev_b32_e32 v16, 16, v27
	v_and_b32_e32 v17, 0xffff0000, v27
	v_pk_fma_f32 v[18:19], v[4:5], v[12:13], v[18:19]
	v_pk_fma_f32 v[20:21], v[0:1], v[20:21], v[8:9]
	v_pk_fma_f32 v[18:19], v[6:7], v[16:17], v[18:19]
	v_pk_fma_f32 v[20:21], v[2:3], v[12:13], v[20:21]
	v_mul_f32_e32 v22, 0xbfb8aa3b, v18
	v_mul_f32_e32 v23, 0xbfb8aa3b, v19
	v_exp_f32_e32 v22, v22
	v_exp_f32_e32 v23, v23
	ds_write2_b32 v25, v14, v15 offset0:6 offset1:42
	v_lshlrev_b32_e32 v14, 16, v26
	v_add_f32_e32 v22, 1.0, v22
	v_add_f32_e32 v23, 1.0, v23
	v_rcp_f32_e32 v22, v22
	v_rcp_f32_e32 v23, v23
	v_and_b32_e32 v15, 0xffff0000, v26
	v_pk_fma_f32 v[20:21], v[4:5], v[16:17], v[20:21]
	v_pk_mul_f32 v[18:19], v[18:19], v[22:23]
	v_pk_fma_f32 v[20:21], v[6:7], v[14:15], v[20:21]
	s_nop 0
	v_mul_f32_e32 v22, 0xbfb8aa3b, v20
	v_mul_f32_e32 v23, 0xbfb8aa3b, v21
	v_exp_f32_e32 v22, v22
	v_exp_f32_e32 v23, v23
	v_add_f32_e32 v22, 1.0, v22
	v_add_f32_e32 v23, 1.0, v23
	v_rcp_f32_e32 v22, v22
	v_rcp_f32_e32 v23, v23
	s_nop 0
	v_pk_mul_f32 v[20:21], v[20:21], v[22:23]
	s_and_saveexec_b64 s[30:31], s[40:41]
	s_cbranch_execz .LBB0_399
	ds_read_b64 v[22:23], v24 offset:56
	s_waitcnt lgkmcnt(0)
	v_pk_mul_f32 v[18:19], v[18:19], v[22:23] op_sel_hi:[1,0]
	v_pk_mul_f32 v[20:21], v[20:21], v[22:23] op_sel:[0,1]
	s_branch .LBB0_399

.LBB0_565:
	s_waitcnt vmcnt(0)
	v_readlane_b32 s0, v254, 55
	v_readlane_b32 s46, v254, 57
	v_readlane_b32 s52, v254, 59
	v_readlane_b32 s54, v254, 62
	v_readlane_b32 s56, v255, 0
	v_readlane_b32 s58, v255, 2
	s_barrier
	v_readlane_b32 s2, v254, 54
	v_readlane_b32 s1, v254, 56
	v_readlane_b32 s47, v254, 58
	v_readlane_b32 s53, v254, 60
	v_readlane_b32 s45, v254, 61
	v_readlane_b32 s55, v254, 63
	v_readlane_b32 s57, v255, 1
	v_readlane_b32 s59, v255, 3
	s_cmp_lg_u32 s68, 6
	s_cbranch_scc1 .Lcv2_done
	s_cmp_lt_u32 s2, 128
	s_cbranch_scc1 .Lcv2_done
	s_waitcnt vmcnt(0)
	v_and_b32_e32 v90, 63, v137
	v_lshrrev_b32_e32 v89, 6, v137
	s_nop 0
	v_readfirstlane_b32 s100, v89
	v_and_b32_e32 v84, 31, v90
	v_lshrrev_b32_e32 v86, 5, v90
	v_and_b32_e32 v88, 7, v90
	v_lshrrev_b32_e32 v87, 3, v90
	v_lshlrev_b32_e32 v85, 5, v88
	s_mul_i32 s101, s100, 0x2100
	v_mul_u32_u24_e32 v89, 33, v86
	v_add_u32_e32 v89, v89, v84
	v_lshl_add_u32 v81, v89, 2, s101
	v_mul_u32_u24_e32 v89, 0x108, v88
	v_add_u32_e32 v89, v89, v87
	v_lshl_add_u32 v82, v89, 2, s101
	s_sub_i32 s15, s2, 128
	s_lshl_b32 s15, s15, 3
	s_add_i32 s15, s15, s100
	s_add_i32 s15, s15, 6400
	s_cmp_ge_u32 s15, 11136
	s_cbranch_scc1 .Lcv2_done

.Lcv2_nomask:
	ds_write_b32 v81, v0
	ds_write_b32 v81, v1 offset:264
	ds_write_b32 v81, v2 offset:528
	ds_write_b32 v81, v3 offset:792
	ds_write_b32 v81, v4 offset:1056
	ds_write_b32 v81, v5 offset:1320
	ds_write_b32 v81, v6 offset:1584
	ds_write_b32 v81, v7 offset:1848
	ds_write_b32 v81, v8 offset:2112
	ds_write_b32 v81, v9 offset:2376
	ds_write_b32 v81, v10 offset:2640
	ds_write_b32 v81, v11 offset:2904
	ds_write_b32 v81, v12 offset:3168
	ds_write_b32 v81, v13 offset:3432
	ds_write_b32 v81, v14 offset:3696
	ds_write_b32 v81, v15 offset:3960
	ds_write_b32 v81, v16 offset:4224
	ds_write_b32 v81, v17 offset:4488
	ds_write_b32 v81, v18 offset:4752
	ds_write_b32 v81, v19 offset:5016
	ds_write_b32 v81, v20 offset:5280
	ds_write_b32 v81, v21 offset:5544
	ds_write_b32 v81, v22 offset:5808
	ds_write_b32 v81, v23 offset:6072
	ds_write_b32 v81, v24 offset:6336
	ds_write_b32 v81, v25 offset:6600
	ds_write_b32 v81, v26 offset:6864
	ds_write_b32 v81, v27 offset:7128
	ds_write_b32 v81, v28 offset:7392
	ds_write_b32 v81, v29 offset:7656
	ds_write_b32 v81, v30 offset:7920
	ds_write_b32 v81, v31 offset:8184
	ds_read2_b32 v[40:41], v82 offset1:33
	ds_read2_b32 v[42:43], v82 offset0:66 offset1:99
	ds_read2_b32 v[44:45], v82 offset0:132 offset1:165
	ds_read2_b32 v[46:47], v82 offset0:198 offset1:231
	ds_read2_b32 v[48:49], v82 offset0:8 offset1:41
	ds_read2_b32 v[50:51], v82 offset0:74 offset1:107
	ds_read2_b32 v[52:53], v82 offset0:140 offset1:173
	ds_read2_b32 v[54:55], v82 offset0:206 offset1:239
	ds_read2_b32 v[56:57], v82 offset0:16 offset1:49
	ds_read2_b32 v[58:59], v82 offset0:82 offset1:115
	ds_read2_b32 v[60:61], v82 offset0:148 offset1:181
	ds_read2_b32 v[62:63], v82 offset0:214 offset1:247
	ds_read2_b32 v[64:65], v82 offset0:24 offset1:57
	ds_read2_b32 v[66:67], v82 offset0:90 offset1:123
	ds_read2_b32 v[68:69], v82 offset0:156 offset1:189
	ds_read2_b32 v[70:71], v82 offset0:222 offset1:255
	s_waitcnt lgkmcnt(0)
	v_mul_f32_e32 v40, v32, v40
	v_mul_f32_e32 v41, v33, v41
	v_mul_f32_e32 v42, v34, v42
	v_mul_f32_e32 v43, v35, v43
	v_mul_f32_e32 v44, v36, v44
	v_mul_f32_e32 v45, v37, v45
	v_mul_f32_e32 v46, v38, v46
	v_mul_f32_e32 v47, v39, v47
	v_cvt_pk_bf16_f32 v72, v40, v41
	v_cvt_pk_bf16_f32 v73, v42, v43
	v_cvt_pk_bf16_f32 v74, v44, v45
	v_cvt_pk_bf16_f32 v75, v46, v47
	global_store_dwordx4 v83, v[72:75], s[28:29]
	v_add_u32_e32 v83, s101, v83
	v_mul_f32_e32 v48, v32, v48
	v_mul_f32_e32 v49, v33, v49
	v_mul_f32_e32 v50, v34, v50
	v_mul_f32_e32 v51, v35, v51
	v_mul_f32_e32 v52, v36, v52
	v_mul_f32_e32 v53, v37, v53
	v_mul_f32_e32 v54, v38, v54
	v_mul_f32_e32 v55, v39, v55
	v_cvt_pk_bf16_f32 v76, v48, v49
	v_cvt_pk_bf16_f32 v77, v50, v51
	v_cvt_pk_bf16_f32 v78, v52, v53
	v_cvt_pk_bf16_f32 v79, v54, v55
	global_store_dwordx4 v83, v[76:79], s[28:29]
	v_add_u32_e32 v83, s101, v83
	v_mul_f32_e32 v56, v32, v56
	v_mul_f32_e32 v57, v33, v57
	v_mul_f32_e32 v58, v34, v58
	v_mul_f32_e32 v59, v35, v59
	v_mul_f32_e32 v60, v36, v60
	v_mul_f32_e32 v61, v37, v61
	v_mul_f32_e32 v62, v38, v62
	v_mul_f32_e32 v63, v39, v63
	v_cvt_pk_bf16_f32 v72, v56, v57
	v_cvt_pk_bf16_f32 v73, v58, v59
	v_cvt_pk_bf16_f32 v74, v60, v61
	v_cvt_pk_bf16_f32 v75, v62, v63
	global_store_dwordx4 v83, v[72:75], s[28:29]
	v_add_u32_e32 v83, s101, v83
	v_mul_f32_e32 v64, v32, v64
	v_mul_f32_e32 v65, v33, v65
	v_mul_f32_e32 v66, v34, v66
	v_mul_f32_e32 v67, v35, v67
	v_mul_f32_e32 v68, v36, v68
	v_mul_f32_e32 v69, v37, v69
	v_mul_f32_e32 v70, v38, v70
	v_mul_f32_e32 v71, v39, v71
	v_cvt_pk_bf16_f32 v76, v64, v65
	v_cvt_pk_bf16_f32 v77, v66, v67
	v_cvt_pk_bf16_f32 v78, v68, v69
	v_cvt_pk_bf16_f32 v79, v70, v71
	global_store_dwordx4 v83, v[76:79], s[28:29]
	s_add_i32 s15, s15, 1024
	s_cmp_lt_u32 s15, 11136
	s_cbranch_scc1 .Lcv2_loop
.Lcv2_done:
	s_cmp_lg_u32 s68, 13
	s_cbranch_scc1 .Lcv3_done
	s_cmp_lt_u32 s2, 128
	s_cbranch_scc1 .Lcv3_done
	s_waitcnt vmcnt(0)
	v_and_b32_e32 v90, 63, v137
	v_lshrrev_b32_e32 v89, 6, v137
	s_nop 0
	v_readfirstlane_b32 s100, v89
	v_and_b32_e32 v84, 31, v90
	v_lshrrev_b32_e32 v86, 5, v90
	v_and_b32_e32 v88, 7, v90
	v_lshrrev_b32_e32 v87, 3, v90
	v_lshlrev_b32_e32 v85, 5, v88
	s_mul_i32 s101, s100, 0x2100
	v_mul_u32_u24_e32 v89, 33, v86
	v_add_u32_e32 v89, v89, v84
	v_lshl_add_u32 v81, v89, 2, s101
	v_mul_u32_u24_e32 v89, 0x108, v88
	v_add_u32_e32 v89, v89, v87
	v_lshl_add_u32 v82, v89, 2, s101
	s_sub_i32 s15, s2, 128
	s_lshl_b32 s15, s15, 3
	s_add_i32 s15, s15, s100
	s_add_i32 s15, s15, 11136
	s_cmp_ge_u32 s15, 12544
	s_cbranch_scc1 .Lcv3_done
